# interleaved exp/PV fast path in all five flash loops (adds FoX and compressed-branch pass 1)
# speedup vs baseline: 1.0380x; 1.0044x over previous
; template <int MODE, int DK, bool PASS2> ...
;     ...
;             if (active) {
;                 f32x16 s0, s1;
;                 if (MODE == M_FOX) {
;                     const LAS float* ct = (const LAS float*)(lds + F_CT + buf * 256) + 8 * g;
; #pragma unroll
;                     for (int q4 = 0; q4 < 4; ++q4) {
;                         const f32x4 a = *(const LAS f32x4*)(ct + (q4 >> 1) * 16 + (q4 & 1) * 4), b = *(const LAS f32x4*)(ct + 32 + (q4 >> 1) * 16 + (q4 & 1) * 4);
; #pragma unroll
;                         for (int e = 0; e < 4; ++e) { s0[q4 * 4 + e] = a[e]; s1[q4 * 4 + e] = b[e]; }
;                     }
;                 } else { s0 = (f32x16)(0.f); s1 = (f32x16)(0.f); }
;                 const LAS unsigned char* kb = lds + F_KB0 + buf * F_KBS + g * 16 + prow * KSTR;
;                 __builtin_amdgcn_s_setprio(1);
; #pragma unroll
;                 for (int kk = 0; kk < DK / 16; ++kk) {
;                     const bf16x8 a0 = *(const LAS bf16x8*)(kb + kk * 32);
;                     const bf16x8 a1 = *(const LAS bf16x8*)(kb + 32 * KSTR + kk * 32);
;                     s0 = mfma32(a0, qf[kk], s0); s1 = mfma32(a1, qf[kk], s1);
;                 }
;                 __builtin_amdgcn_s_setprio(0);
;                 const bool need_causal = pos_max > t_wmin;
;                 const bool need_bias = (MODE != M_FOX) && ((t_wmin - pos_max) < 128);
;                 const bool need_win = (MODE == M_WIN) && (t_wmax - pos_min >= 512);
;                 if (!PASS2 && !(need_causal || need_bias || need_win)) {
;                     float mx = fmaxf(s0[0], s1[0]);
; #pragma unroll
;                     for (int r = 1; r < 16; ++r) mx = fmax3(mx, s0[r], s1[r]);
;                     if (MODE == M_SLC) mx = selbit ? mx : NEG;
;                     mx = xhalf_max(mx);
;                     const float mxs = mx * sl2;
;                     const float mn = (mxs > m_run + 8.0f) ? mxs : m_run;
;                     const float alpha = fexp2(m_run - mn);
;                     m_run = mn;
;                     float nm = -mn;
;                     if (MODE == M_SLC) nm = selbit ? nm : -__builtin_inff();
;                     float ps0 = 0.f, ps1 = 0.f;
; #pragma unroll
;                     for (int r = 0; r < 16; ++r) {
;                         s0[r] = fexp2(__builtin_fmaf(s0[r], sl2, nm)); s1[r] = fexp2(__builtin_fmaf(s1[r], sl2, nm));
.LBB0_942:
	s_sub_i32 s24, s87, 63
	v_cmp_le_i32_e32 vcc, s24, v227
	v_mov_b32_e32 v2, 0
	s_and_saveexec_b64 s[50:51], vcc
	s_cbranch_execz .LBB0_954
	v_lshl_add_u32 v2, s86, 8, v229
	ds_read_b128 v[98:101], v2
	ds_read_b128 v[102:105], v2 offset:16
	ds_read_b128 v[82:85], v2 offset:128
	ds_read_b128 v[86:89], v2 offset:144
	ds_read_b128 v[106:109], v2 offset:64
	ds_read_b128 v[110:113], v2 offset:80
	ds_read_b128 v[90:93], v2 offset:192
	ds_read_b128 v[94:97], v2 offset:208
	s_mul_i32 s24, s86, 0x4400
	v_add_u32_e32 v2, s24, v230
	s_setprio 1
	ds_read_b128 v[4:7], v2
	ds_read_b128 v[8:11], v2 offset:32
	s_waitcnt lgkmcnt(1)
	v_mfma_f32_32x32x16_bf16 v[98:113], v[4:7], v[146:149], v[98:113]
	ds_read_b128 v[4:7], v2 offset:8704
	ds_read_b128 v[12:15], v2 offset:8736
	s_waitcnt lgkmcnt(1)
	v_mfma_f32_32x32x16_bf16 v[82:97], v[4:7], v[146:149], v[82:97]
	v_mfma_f32_32x32x16_bf16 v[98:113], v[8:11], v[150:153], v[98:113]
	ds_read_b128 v[4:7], v2 offset:64
	ds_read_b128 v[8:11], v2 offset:96
	s_waitcnt lgkmcnt(2)
	v_mfma_f32_32x32x16_bf16 v[82:97], v[12:15], v[150:153], v[82:97]
	s_waitcnt lgkmcnt(1)
	v_mfma_f32_32x32x16_bf16 v[98:113], v[4:7], v[154:157], v[98:113]
	ds_read_b128 v[4:7], v2 offset:8768
	ds_read_b128 v[12:15], v2 offset:8800
	s_waitcnt lgkmcnt(1)
	v_mfma_f32_32x32x16_bf16 v[82:97], v[4:7], v[154:157], v[82:97]
	v_mfma_f32_32x32x16_bf16 v[98:113], v[8:11], v[158:161], v[98:113]
	ds_read_b128 v[4:7], v2 offset:128
	ds_read_b128 v[8:11], v2 offset:160
	s_waitcnt lgkmcnt(2)
	v_mfma_f32_32x32x16_bf16 v[82:97], v[12:15], v[158:161], v[82:97]
	s_waitcnt lgkmcnt(1)
	v_mfma_f32_32x32x16_bf16 v[98:113], v[4:7], v[162:165], v[98:113]
	ds_read_b128 v[4:7], v2 offset:8832
	ds_read_b128 v[12:15], v2 offset:8864
	s_waitcnt lgkmcnt(1)
	v_mfma_f32_32x32x16_bf16 v[82:97], v[4:7], v[162:165], v[82:97]
	v_mfma_f32_32x32x16_bf16 v[98:113], v[8:11], v[166:169], v[98:113]
	ds_read_b128 v[4:7], v2 offset:192
	ds_read_b128 v[8:11], v2 offset:224
	s_waitcnt lgkmcnt(2)
	v_mfma_f32_32x32x16_bf16 v[82:97], v[12:15], v[166:169], v[82:97]
	s_waitcnt lgkmcnt(1)
	v_mfma_f32_32x32x16_bf16 v[98:113], v[4:7], v[170:173], v[98:113]
	ds_read_b128 v[4:7], v2 offset:8896
	ds_read_b128 v[12:15], v2 offset:8928
	s_waitcnt lgkmcnt(1)
	v_mfma_f32_32x32x16_bf16 v[82:97], v[4:7], v[170:173], v[82:97]
	v_mfma_f32_32x32x16_bf16 v[98:113], v[8:11], v[174:177], v[98:113]
	s_waitcnt lgkmcnt(0)
	v_mfma_f32_32x32x16_bf16 v[82:97], v[12:15], v[174:177], v[82:97]
	s_setprio 0
	v_cmp_le_i32_e32 vcc, s87, v216
	v_add_f32_e32 v2, 0x41000000, v239
	s_and_saveexec_b64 s[52:53], vcc
	s_xor_b64 s[52:53], exec, s[52:53]
	s_cbranch_execz .LBB0_947
	s_cmp_eq_u64 s[52:53], 0
	s_cbranch_scc1 .Lfast_fox
	s_nop 3
	v_max_f32_e32 v4, v98, v98
	s_nop 0
	v_max_f32_e32 v5, v82, v82
	v_max_f32_e32 v4, v4, v5
	v_max3_f32 v4, v4, v99, v83
	s_nop 0
	v_max3_f32 v4, v4, v100, v84
	s_nop 0
	v_max3_f32 v4, v4, v101, v85
	s_nop 0
	v_max3_f32 v4, v4, v102, v86
	s_nop 0
	v_max3_f32 v4, v4, v103, v87
	s_nop 0
	v_max3_f32 v4, v4, v104, v88
	s_nop 0
	v_max3_f32 v4, v4, v105, v89
	s_nop 0
	v_max3_f32 v4, v4, v106, v90
	s_nop 0
	v_max3_f32 v4, v4, v107, v91
	s_nop 0
	v_max3_f32 v4, v4, v108, v92
	s_nop 0
	v_max3_f32 v4, v4, v109, v93
	s_nop 0
	v_max3_f32 v4, v4, v110, v94
	s_nop 0
	v_max3_f32 v4, v4, v111, v95
	s_nop 0
	v_max3_f32 v4, v4, v112, v96
	s_nop 0
	v_max3_f32 v4, v4, v113, v97
	s_nop 0
	v_mov_b32_e32 v5, v4
	s_nop 1
	v_permlane32_swap_b32_e32 v4, v5
	v_max_f32_e32 v5, v5, v5
	v_max_f32_e32 v4, v4, v4
	v_max_f32_e32 v4, v4, v5
	v_mul_f32_e32 v4, 0x3e0293ee, v4
	v_cmp_gt_f32_e32 vcc, v4, v2
	s_nop 1
	v_cndmask_b32_e32 v4, v239, v4, vcc
	v_sub_f32_e32 v2, v239, v4
	v_exp_f32_e32 v2, v2
	s_nop 0
	v_cmp_neq_f32_e32 vcc, 1.0, v2
	s_cbranch_vccz .LBB0_946
	v_pk_mul_f32 v[80:81], v[80:81], v[2:3] op_sel_hi:[1,0]
	v_pk_mul_f32 v[78:79], v[78:79], v[2:3] op_sel_hi:[1,0]
	v_pk_mul_f32 v[76:77], v[76:77], v[2:3] op_sel_hi:[1,0]
	v_pk_mul_f32 v[74:75], v[74:75], v[2:3] op_sel_hi:[1,0]
	v_pk_mul_f32 v[72:73], v[72:73], v[2:3] op_sel_hi:[1,0]
	v_pk_mul_f32 v[70:71], v[70:71], v[2:3] op_sel_hi:[1,0]
	v_pk_mul_f32 v[68:69], v[68:69], v[2:3] op_sel_hi:[1,0]
	v_pk_mul_f32 v[66:67], v[66:67], v[2:3] op_sel_hi:[1,0]
	v_pk_mul_f32 v[64:65], v[64:65], v[2:3] op_sel_hi:[1,0]
	v_pk_mul_f32 v[62:63], v[62:63], v[2:3] op_sel_hi:[1,0]
	v_pk_mul_f32 v[60:61], v[60:61], v[2:3] op_sel_hi:[1,0]
	v_pk_mul_f32 v[58:59], v[58:59], v[2:3] op_sel_hi:[1,0]
	v_pk_mul_f32 v[56:57], v[56:57], v[2:3] op_sel_hi:[1,0]
	v_pk_mul_f32 v[54:55], v[54:55], v[2:3] op_sel_hi:[1,0]
	v_pk_mul_f32 v[52:53], v[52:53], v[2:3] op_sel_hi:[1,0]
	v_pk_mul_f32 v[50:51], v[50:51], v[2:3] op_sel_hi:[1,0]
	v_pk_mul_f32 v[48:49], v[48:49], v[2:3] op_sel_hi:[1,0]
	v_pk_mul_f32 v[46:47], v[46:47], v[2:3] op_sel_hi:[1,0]
	v_pk_mul_f32 v[44:45], v[44:45], v[2:3] op_sel_hi:[1,0]
	v_pk_mul_f32 v[42:43], v[42:43], v[2:3] op_sel_hi:[1,0]
	v_pk_mul_f32 v[40:41], v[40:41], v[2:3] op_sel_hi:[1,0]
	v_pk_mul_f32 v[38:39], v[38:39], v[2:3] op_sel_hi:[1,0]
	v_pk_mul_f32 v[36:37], v[36:37], v[2:3] op_sel_hi:[1,0]
	v_pk_mul_f32 v[34:35], v[34:35], v[2:3] op_sel_hi:[1,0]
	v_pk_mul_f32 v[32:33], v[32:33], v[2:3] op_sel_hi:[1,0]
	v_pk_mul_f32 v[30:31], v[30:31], v[2:3] op_sel_hi:[1,0]
	v_pk_mul_f32 v[28:29], v[28:29], v[2:3] op_sel_hi:[1,0]
	v_pk_mul_f32 v[26:27], v[26:27], v[2:3] op_sel_hi:[1,0]
	v_pk_mul_f32 v[24:25], v[24:25], v[2:3] op_sel_hi:[1,0]
	v_pk_mul_f32 v[22:23], v[22:23], v[2:3] op_sel_hi:[1,0]
	v_pk_mul_f32 v[20:21], v[20:21], v[2:3] op_sel_hi:[1,0]
	v_pk_mul_f32 v[18:19], v[18:19], v[2:3] op_sel_hi:[1,0]

; template <int MODE, int DK, bool PASS2> ...
;     ...
;                     if (MODE == M_FOX) {
;                         if (has) { const float cn = cg2[jn * 64 + 63]; dead = __builtin_amdgcn_ballot_w64(!((qnb - cn) - m_run < -160.0f)) == 0ull; }
;                     }
.Lpostpv_fox:
	s_and_b64 vcc, exec, s[10:11]
	v_mov_b32_e32 v2, 0
	s_cbranch_vccnz .LBB0_953
	s_add_i32 s24, s87, 0xffffff81
	s_lshl_b64 s[52:53], s[24:25], 2
	s_add_u32 s52, s36, s52
	s_addc_u32 s53, s37, s53
	global_load_dword v2, v3, s[52:53] offset:252
	s_waitcnt vmcnt(0)
	v_sub_f32_e32 v2, v226, v2
	v_sub_f32_e32 v2, v2, v4
	v_cmp_ngt_f32_e32 vcc, s84, v2
	s_cmp_eq_u64 vcc, 0
	s_cselect_b64 s[52:53], -1, 0
	v_cndmask_b32_e64 v2, 0, 1, s[52:53]

; #define LAS __attribute__((address_space(3)))
; __device__ __forceinline__ float fexp2(float x) { return __builtin_amdgcn_exp2f(x); }
; __device__ __forceinline__ float fmax3(float a, float b, float c) { float d; asm("v_max3_f32 %0, %1, %2, %3" : "=v"(d) : "v"(a), "v"(b), "v"(c)); return d; }
; template <int MODE, int DK, bool PASS2> ...
;     ...
;                     float mx = fmaxf(s0[0], s1[0]);
; #pragma unroll
;                     for (int r = 1; r < 16; ++r) mx = fmax3(mx, s0[r], s1[r]);
;                     if (MODE == M_SLC) mx = selbit ? mx : NEG;
;                     mx = xhalf_max(mx);
;                     const float mxs = mx * sl2;
;                     const float mn = (mxs > m_run + 8.0f) ? mxs : m_run;
;                     const float alpha = fexp2(m_run - mn);
;                     m_run = mn;
;                     float nm = -mn;
;                     if (MODE == M_SLC) nm = selbit ? nm : -__builtin_inff();
;                     float ps0 = 0.f, ps1 = 0.f;
; #pragma unroll
;                     for (int r = 0; r < 16; ++r) {
;                         s0[r] = fexp2(__builtin_fmaf(s0[r], sl2, nm)); s1[r] = fexp2(__builtin_fmaf(s1[r], sl2, nm));
;                         ps0 += s0[r]; ps1 += s1[r];
;                     }
;                     l_run = l_run * alpha + (ps0 + ps1);
;                     if (__builtin_amdgcn_ballot_w64(alpha != 1.0f) != 0ull) {
; #pragma unroll
;                         for (int db = 0; db < 4; ++db)
; #pragma unroll
;                             for (int r = 0; r < 16; ++r) O[db][r] *= alpha;
;                     }
;     ...
;                     const LAS unsigned char* vb = lds + F_VB0 + buf * F_VBS + ql * 144 + g * 16;
;                     __builtin_amdgcn_s_setprio(1);
; #pragma unroll
;                     for (int db = 0; db < 4; ++db)
; #pragma unroll
;                         for (int k2 = 0; k2 < 4; ++k2) {
;                             const bf16x8 vf = *(const LAS bf16x8*)(vb + db * 32 * 144 + k2 * 32);
.Lfast_fox:
	s_mul_i32 s98, s86, 0x4800
	v_add_u32_e32 v252, s98, v231
	ds_read_b128 v[240:243], v252 offset:34816
	ds_read_b128 v[244:247], v252 offset:39424
	ds_read_b128 v[248:251], v252 offset:44032
	v_max_f32_e32 v124, v98, v99
	v_max_f32_e32 v125, v82, v83
	v_max3_f32 v124, v124, v100, v101
	v_max3_f32 v125, v125, v84, v85
	v_max3_f32 v124, v124, v102, v103
	v_max3_f32 v125, v125, v86, v87
	v_max3_f32 v124, v124, v104, v105
	v_max3_f32 v125, v125, v88, v89
	v_max3_f32 v124, v124, v106, v107
	v_max3_f32 v125, v125, v90, v91
	v_max3_f32 v124, v124, v108, v109
	v_max3_f32 v125, v125, v92, v93
	v_max3_f32 v124, v124, v110, v111
	v_max3_f32 v125, v125, v94, v95
	v_max3_f32 v124, v124, v112, v113
	v_max3_f32 v125, v125, v96, v97
	v_max_f32_e32 v124, v124, v125
	v_mov_b32_e32 v125, v124
	s_nop 1
	v_permlane32_swap_b32_e32 v124, v125
	v_max_f32_e32 v124, v124, v125
	v_mul_f32_e32 v124, 0x3e0293ee, v124
	v_cmp_gt_f32_e32 vcc, v124, v2
	s_nop 1
	v_cndmask_b32_e32 v4, v239, v124, vcc
	v_sub_f32_e32 v125, v239, v4
	v_exp_f32_e32 v2, v125
	s_nop 0
	v_cmp_neq_f32_e32 vcc, 1.0, v2
	s_cbranch_vccz .Lfast_fox_norescale
	v_pk_mul_f32 v[80:81], v[80:81], v[2:3] op_sel_hi:[1,0]
	v_pk_mul_f32 v[78:79], v[78:79], v[2:3] op_sel_hi:[1,0]
	v_pk_mul_f32 v[76:77], v[76:77], v[2:3] op_sel_hi:[1,0]
	v_pk_mul_f32 v[74:75], v[74:75], v[2:3] op_sel_hi:[1,0]
	v_pk_mul_f32 v[72:73], v[72:73], v[2:3] op_sel_hi:[1,0]
	v_pk_mul_f32 v[70:71], v[70:71], v[2:3] op_sel_hi:[1,0]
	v_pk_mul_f32 v[68:69], v[68:69], v[2:3] op_sel_hi:[1,0]
	v_pk_mul_f32 v[66:67], v[66:67], v[2:3] op_sel_hi:[1,0]
	v_pk_mul_f32 v[64:65], v[64:65], v[2:3] op_sel_hi:[1,0]
	v_pk_mul_f32 v[62:63], v[62:63], v[2:3] op_sel_hi:[1,0]
	v_pk_mul_f32 v[60:61], v[60:61], v[2:3] op_sel_hi:[1,0]
	v_pk_mul_f32 v[58:59], v[58:59], v[2:3] op_sel_hi:[1,0]
	v_pk_mul_f32 v[56:57], v[56:57], v[2:3] op_sel_hi:[1,0]
	v_pk_mul_f32 v[54:55], v[54:55], v[2:3] op_sel_hi:[1,0]
	v_pk_mul_f32 v[52:53], v[52:53], v[2:3] op_sel_hi:[1,0]
	v_pk_mul_f32 v[50:51], v[50:51], v[2:3] op_sel_hi:[1,0]
	v_pk_mul_f32 v[48:49], v[48:49], v[2:3] op_sel_hi:[1,0]
	v_pk_mul_f32 v[46:47], v[46:47], v[2:3] op_sel_hi:[1,0]
	v_pk_mul_f32 v[44:45], v[44:45], v[2:3] op_sel_hi:[1,0]
	v_pk_mul_f32 v[42:43], v[42:43], v[2:3] op_sel_hi:[1,0]
	v_pk_mul_f32 v[40:41], v[40:41], v[2:3] op_sel_hi:[1,0]
	v_pk_mul_f32 v[38:39], v[38:39], v[2:3] op_sel_hi:[1,0]
	v_pk_mul_f32 v[36:37], v[36:37], v[2:3] op_sel_hi:[1,0]
	v_pk_mul_f32 v[34:35], v[34:35], v[2:3] op_sel_hi:[1,0]
	v_pk_mul_f32 v[32:33], v[32:33], v[2:3] op_sel_hi:[1,0]
	v_pk_mul_f32 v[30:31], v[30:31], v[2:3] op_sel_hi:[1,0]
	v_pk_mul_f32 v[28:29], v[28:29], v[2:3] op_sel_hi:[1,0]
	v_pk_mul_f32 v[26:27], v[26:27], v[2:3] op_sel_hi:[1,0]
	v_pk_mul_f32 v[24:25], v[24:25], v[2:3] op_sel_hi:[1,0]
	v_pk_mul_f32 v[22:23], v[22:23], v[2:3] op_sel_hi:[1,0]
	v_pk_mul_f32 v[20:21], v[20:21], v[2:3] op_sel_hi:[1,0]
	v_pk_mul_f32 v[18:19], v[18:19], v[2:3] op_sel_hi:[1,0]
; #define LAS __attribute__((address_space(3)))
; __device__ __forceinline__ unsigned pack2(float lo, float hi) { unsigned r; asm volatile("v_cvt_pk_bf16_f32 %0, %1, %2" : "=v"(r) : "v"(lo), "v"(hi)); return r; }
; __device__ __forceinline__ float fexp2(float x) { return __builtin_amdgcn_exp2f(x); }
; __device__ __forceinline__ f32x16 mfma32(bf16x8 a, bf16x8 b, f32x16 c) { return __builtin_amdgcn_mfma_f32_32x32x16_bf16(a, b, c, 0, 0, 0); }
; template <int MODE, int DK, bool PASS2> ...
;     ...
;                     float ps0 = 0.f, ps1 = 0.f;
; #pragma unroll
;                     for (int r = 0; r < 16; ++r) {
;                         s0[r] = fexp2(__builtin_fmaf(s0[r], sl2, nm)); s1[r] = fexp2(__builtin_fmaf(s1[r], sl2, nm));
;                         ps0 += s0[r]; ps1 += s1[r];
;                     }
;                     l_run = l_run * alpha + (ps0 + ps1);
;     ...
;                 if (!PASS2) {
;                     bf16x8 pf[4];
; #pragma unroll
;                     for (int k2 = 0; k2 < 4; ++k2) {
;                         u32x4 pk;
; #pragma unroll
;                         for (int e = 0; e < 4; ++e) pk[e] = (k2 < 2) ? pack2(s0[(k2 & 1) * 8 + 2 * e], s0[(k2 & 1) * 8 + 2 * e + 1]) : pack2(s1[(k2 & 1) * 8 + 2 * e], s1[(k2 & 1) * 8 + 2 * e + 1]);
;                         pf[k2] = __builtin_bit_cast(bf16x8, pk);
;                     }
;                     const LAS unsigned char* vb = lds + F_VB0 + buf * F_VBS + ql * 144 + g * 16;
;                     __builtin_amdgcn_s_setprio(1);
; #pragma unroll
;                     for (int db = 0; db < 4; ++db)
; #pragma unroll
;                         for (int k2 = 0; k2 < 4; ++k2) {
;                             const bf16x8 vf = *(const LAS bf16x8*)(vb + db * 32 * 144 + k2 * 32);
;                             O[db] = mfma32(vf, pf[k2], O[db]);
;                             if (k2 == 3 && (db & 1)) __builtin_amdgcn_sched_barrier(0);
;                         }
;                     __builtin_amdgcn_s_setprio(0);
;                     if (MODE == M_FOX) {
;                         if (has) { const float cn = cg2[jn * 64 + 63]; dead = __builtin_amdgcn_ballot_w64(!((qnb - cn) - m_run < -160.0f)) == 0ull; }
;                     }
.Lfast_fox_norescale:
	v_fma_f32 v118, v98, s83, -v4
	v_fma_f32 v119, v99, s83, -v4
	v_exp_f32_e32 v6, v118
	v_exp_f32_e32 v7, v119
	v_fma_f32 v120, v100, s83, -v4
	v_fma_f32 v121, v101, s83, -v4
	v_exp_f32_e32 v8, v120
	v_exp_f32_e32 v9, v121
	v_add_f32_e32 v122, v6, v7
	v_fma_f32 v118, v102, s83, -v4
	v_fma_f32 v119, v103, s83, -v4
	v_exp_f32_e32 v114, v118
	v_exp_f32_e32 v115, v119
	v_cvt_pk_bf16_f32 v98, v6, v7
	v_add_f32_e32 v122, v122, v8
	v_fma_f32 v120, v104, s83, -v4
	v_add_f32_e32 v122, v122, v9
	v_fma_f32 v121, v105, s83, -v4
	v_exp_f32_e32 v116, v120
	v_exp_f32_e32 v117, v121
	v_cvt_pk_bf16_f32 v99, v8, v9
	v_add_f32_e32 v122, v122, v114
	v_add_f32_e32 v122, v122, v115
	v_cvt_pk_bf16_f32 v100, v114, v115
	v_add_f32_e32 v122, v122, v116
	v_add_f32_e32 v122, v122, v117
	v_cvt_pk_bf16_f32 v101, v116, v117
	s_setprio 1
	v_fma_f32 v118, v106, s83, -v4
	v_fma_f32 v119, v107, s83, -v4
	s_waitcnt lgkmcnt(2)
	v_mfma_f32_32x32x16_bf16 v[66:81], v[240:243], v[98:101], v[66:81]
	v_exp_f32_e32 v6, v118
	v_exp_f32_e32 v7, v119
	v_fma_f32 v120, v108, s83, -v4
	v_fma_f32 v121, v109, s83, -v4
	v_exp_f32_e32 v8, v120
	v_exp_f32_e32 v9, v121
	v_add_f32_e32 v122, v122, v6
	s_waitcnt lgkmcnt(1)
	v_mfma_f32_32x32x16_bf16 v[50:65], v[244:247], v[98:101], v[50:65]
	ds_read_b128 v[240:243], v252 offset:48640
	v_fma_f32 v118, v110, s83, -v4
	v_add_f32_e32 v122, v122, v7
	v_fma_f32 v119, v111, s83, -v4
	v_exp_f32_e32 v114, v118
	v_exp_f32_e32 v115, v119
	v_cvt_pk_bf16_f32 v106, v6, v7
	v_add_f32_e32 v122, v122, v8
	s_waitcnt lgkmcnt(1)
	v_mfma_f32_32x32x16_bf16 v[34:49], v[248:251], v[98:101], v[34:49]
	ds_read_b128 v[244:247], v252 offset:34848
	v_fma_f32 v120, v112, s83, -v4
	v_add_f32_e32 v122, v122, v9
	v_fma_f32 v121, v113, s83, -v4
	v_exp_f32_e32 v116, v120
	v_exp_f32_e32 v117, v121
	v_cvt_pk_bf16_f32 v107, v8, v9
	v_add_f32_e32 v122, v122, v114
	s_waitcnt lgkmcnt(1)
	v_mfma_f32_32x32x16_bf16 v[18:33], v[240:243], v[98:101], v[18:33]
	ds_read_b128 v[248:251], v252 offset:39456
	v_add_f32_e32 v122, v122, v115
	v_cvt_pk_bf16_f32 v108, v114, v115
	v_add_f32_e32 v122, v122, v116
	v_add_f32_e32 v122, v122, v117
	v_cvt_pk_bf16_f32 v109, v116, v117
	v_fma_f32 v118, v82, s83, -v4
	v_fma_f32 v119, v83, s83, -v4
	s_waitcnt lgkmcnt(1)
	v_mfma_f32_32x32x16_bf16 v[66:81], v[244:247], v[106:109], v[66:81]
	ds_read_b128 v[240:243], v252 offset:44064
	v_exp_f32_e32 v6, v118
	v_exp_f32_e32 v7, v119
	v_fma_f32 v120, v84, s83, -v4
	v_fma_f32 v121, v85, s83, -v4
	v_exp_f32_e32 v8, v120
	v_exp_f32_e32 v9, v121
	v_add_f32_e32 v123, v6, v7
	s_waitcnt lgkmcnt(1)
	v_mfma_f32_32x32x16_bf16 v[50:65], v[248:251], v[106:109], v[50:65]
	ds_read_b128 v[244:247], v252 offset:48672
	v_fma_f32 v118, v86, s83, -v4
	v_fma_f32 v119, v87, s83, -v4
	v_exp_f32_e32 v114, v118
	v_exp_f32_e32 v115, v119
	v_cvt_pk_bf16_f32 v82, v6, v7
	v_add_f32_e32 v123, v123, v8
	v_fma_f32 v120, v88, s83, -v4
	s_waitcnt lgkmcnt(1)
	v_mfma_f32_32x32x16_bf16 v[34:49], v[240:243], v[106:109], v[34:49]
	ds_read_b128 v[248:251], v252 offset:34880
	v_add_f32_e32 v123, v123, v9
	v_fma_f32 v121, v89, s83, -v4
	v_exp_f32_e32 v116, v120
	v_exp_f32_e32 v117, v121
	v_cvt_pk_bf16_f32 v83, v8, v9
	v_add_f32_e32 v123, v123, v114
	v_add_f32_e32 v123, v123, v115
	s_waitcnt lgkmcnt(1)
	v_mfma_f32_32x32x16_bf16 v[18:33], v[244:247], v[106:109], v[18:33]
	ds_read_b128 v[240:243], v252 offset:39488
	v_cvt_pk_bf16_f32 v84, v114, v115
	v_add_f32_e32 v123, v123, v116
	v_add_f32_e32 v123, v123, v117
	v_cvt_pk_bf16_f32 v85, v116, v117
	v_fma_f32 v118, v90, s83, -v4
	v_fma_f32 v119, v91, s83, -v4
	s_waitcnt lgkmcnt(1)
	v_mfma_f32_32x32x16_bf16 v[66:81], v[248:251], v[82:85], v[66:81]
	ds_read_b128 v[244:247], v252 offset:44096
	v_exp_f32_e32 v6, v118
	v_exp_f32_e32 v7, v119
	v_fma_f32 v120, v92, s83, -v4
	v_fma_f32 v121, v93, s83, -v4
	v_exp_f32_e32 v8, v120
	v_exp_f32_e32 v9, v121
	v_add_f32_e32 v123, v123, v6
	s_waitcnt lgkmcnt(1)
	v_mfma_f32_32x32x16_bf16 v[50:65], v[240:243], v[82:85], v[50:65]
	ds_read_b128 v[248:251], v252 offset:48704
	v_fma_f32 v118, v94, s83, -v4
	v_add_f32_e32 v123, v123, v7
	v_fma_f32 v119, v95, s83, -v4
	v_exp_f32_e32 v114, v118
	v_exp_f32_e32 v115, v119
	v_cvt_pk_bf16_f32 v90, v6, v7
	v_add_f32_e32 v123, v123, v8
	s_waitcnt lgkmcnt(1)
	v_mfma_f32_32x32x16_bf16 v[34:49], v[244:247], v[82:85], v[34:49]
	ds_read_b128 v[240:243], v252 offset:34912
	v_fma_f32 v120, v96, s83, -v4
	v_add_f32_e32 v123, v123, v9
	v_fma_f32 v121, v97, s83, -v4
	v_exp_f32_e32 v116, v120
	v_exp_f32_e32 v117, v121
	v_cvt_pk_bf16_f32 v91, v8, v9
	v_add_f32_e32 v123, v123, v114
	s_waitcnt lgkmcnt(1)
	v_mfma_f32_32x32x16_bf16 v[18:33], v[248:251], v[82:85], v[18:33]
	ds_read_b128 v[244:247], v252 offset:39520
	v_add_f32_e32 v123, v123, v115
	v_cvt_pk_bf16_f32 v92, v114, v115
	v_add_f32_e32 v123, v123, v116
	v_add_f32_e32 v123, v123, v117
	v_cvt_pk_bf16_f32 v93, v116, v117
	v_add_f32_e32 v5, v122, v123
	s_waitcnt lgkmcnt(1)
	v_mfma_f32_32x32x16_bf16 v[66:81], v[240:243], v[90:93], v[66:81]
	ds_read_b128 v[248:251], v252 offset:44128
	v_fmac_f32_e32 v5, v238, v2
	s_waitcnt lgkmcnt(1)
	v_mfma_f32_32x32x16_bf16 v[50:65], v[244:247], v[90:93], v[50:65]
	ds_read_b128 v[240:243], v252 offset:48736
	s_waitcnt lgkmcnt(1)
	v_mfma_f32_32x32x16_bf16 v[34:49], v[248:251], v[90:93], v[34:49]
	s_waitcnt lgkmcnt(0)
	v_mfma_f32_32x32x16_bf16 v[18:33], v[240:243], v[90:93], v[18:33]
	s_setprio 0
	s_branch .Lpostpv_fox

; template <int MODE, int DK, bool PASS2> ...
;     ...
;             if (active) {
;                 f32x16 s0, s1;
;                 if (MODE == M_FOX) {
;                     const LAS float* ct = (const LAS float*)(lds + F_CT + buf * 256) + 8 * g;
; #pragma unroll
;                     for (int q4 = 0; q4 < 4; ++q4) {
;                         const f32x4 a = *(const LAS f32x4*)(ct + (q4 >> 1) * 16 + (q4 & 1) * 4), b = *(const LAS f32x4*)(ct + 32 + (q4 >> 1) * 16 + (q4 & 1) * 4);
; #pragma unroll
;                         for (int e = 0; e < 4; ++e) { s0[q4 * 4 + e] = a[e]; s1[q4 * 4 + e] = b[e]; }
;                     }
;                 } else { s0 = (f32x16)(0.f); s1 = (f32x16)(0.f); }
;                 const LAS unsigned char* kb = lds + F_KB0 + buf * F_KBS + g * 16 + prow * KSTR;
;                 __builtin_amdgcn_s_setprio(1);
; #pragma unroll
;                 for (int kk = 0; kk < DK / 16; ++kk) {
;                     const bf16x8 a0 = *(const LAS bf16x8*)(kb + kk * 32);
;                     const bf16x8 a1 = *(const LAS bf16x8*)(kb + 32 * KSTR + kk * 32);
;                     s0 = mfma32(a0, qf[kk], s0); s1 = mfma32(a1, qf[kk], s1);
;                 }
;                 __builtin_amdgcn_s_setprio(0);
;                 const bool need_causal = pos_max > t_wmin;
;                 const bool need_bias = (MODE != M_FOX) && ((t_wmin - pos_max) < 128);
;                 const bool need_win = (MODE == M_WIN) && (t_wmax - pos_min >= 512);
;                 if (!PASS2 && !(need_causal || need_bias || need_win)) {
;                     float mx = fmaxf(s0[0], s1[0]);
; #pragma unroll
;                     for (int r = 1; r < 16; ++r) mx = fmax3(mx, s0[r], s1[r]);
;                     if (MODE == M_SLC) mx = selbit ? mx : NEG;
;                     mx = xhalf_max(mx);
;                     const float mxs = mx * sl2;
;                     const float mn = (mxs > m_run + 8.0f) ? mxs : m_run;
;                     const float alpha = fexp2(m_run - mn);
;                     m_run = mn;
;                     float nm = -mn;
;                     if (MODE == M_SLC) nm = selbit ? nm : -__builtin_inff();
;                     float ps0 = 0.f, ps1 = 0.f;
; #pragma unroll
;                     for (int r = 0; r < 16; ++r) {
;                         s0[r] = fexp2(__builtin_fmaf(s0[r], sl2, nm)); s1[r] = fexp2(__builtin_fmaf(s1[r], sl2, nm));
.LBB0_2269:
	s_mul_i32 s4, s39, 0x4400
	v_add_u32_e32 v2, s4, v243
	s_setprio 1
	ds_read_b128 v[4:7], v2
	ds_read_b128 v[8:11], v2 offset:32
	s_waitcnt lgkmcnt(1)
	v_mfma_f32_32x32x16_bf16 v[82:97], v[4:7], v[114:117], 0
	ds_read_b128 v[4:7], v2 offset:8704
	ds_read_b128 v[12:15], v2 offset:8736
	s_waitcnt lgkmcnt(1)
	v_mfma_f32_32x32x16_bf16 v[98:113], v[4:7], v[114:117], 0
	v_mfma_f32_32x32x16_bf16 v[82:97], v[8:11], v[118:121], v[82:97]
	ds_read_b128 v[4:7], v2 offset:64
	ds_read_b128 v[8:11], v2 offset:96
	s_waitcnt lgkmcnt(2)
	v_mfma_f32_32x32x16_bf16 v[98:113], v[12:15], v[118:121], v[98:113]
	s_waitcnt lgkmcnt(1)
	v_mfma_f32_32x32x16_bf16 v[82:97], v[4:7], v[122:125], v[82:97]
	ds_read_b128 v[4:7], v2 offset:8768
	ds_read_b128 v[12:15], v2 offset:8800
	s_waitcnt lgkmcnt(1)
	v_mfma_f32_32x32x16_bf16 v[98:113], v[4:7], v[122:125], v[98:113]
	v_mfma_f32_32x32x16_bf16 v[82:97], v[8:11], v[126:129], v[82:97]
	ds_read_b128 v[4:7], v2 offset:128
	ds_read_b128 v[8:11], v2 offset:160
	s_waitcnt lgkmcnt(2)
	v_mfma_f32_32x32x16_bf16 v[98:113], v[12:15], v[126:129], v[98:113]
	s_waitcnt lgkmcnt(1)
	v_mfma_f32_32x32x16_bf16 v[82:97], v[4:7], v[130:133], v[82:97]
	ds_read_b128 v[4:7], v2 offset:8832
	ds_read_b128 v[12:15], v2 offset:8864
	s_waitcnt lgkmcnt(1)
	v_mfma_f32_32x32x16_bf16 v[98:113], v[4:7], v[130:133], v[98:113]
	v_mfma_f32_32x32x16_bf16 v[82:97], v[8:11], v[134:137], v[82:97]
	ds_read_b128 v[4:7], v2 offset:192
	ds_read_b128 v[8:11], v2 offset:224
	s_waitcnt lgkmcnt(2)
	v_mfma_f32_32x32x16_bf16 v[98:113], v[12:15], v[134:137], v[98:113]
	s_waitcnt lgkmcnt(1)
	v_mfma_f32_32x32x16_bf16 v[82:97], v[4:7], v[138:141], v[82:97]
	ds_read_b128 v[4:7], v2 offset:8896
	ds_read_b128 v[12:15], v2 offset:8928
	s_waitcnt lgkmcnt(1)
	v_mfma_f32_32x32x16_bf16 v[98:113], v[4:7], v[138:141], v[98:113]
	v_mfma_f32_32x32x16_bf16 v[82:97], v[8:11], v[142:145], v[82:97]
	s_waitcnt lgkmcnt(0)
	v_mfma_f32_32x32x16_bf16 v[98:113], v[12:15], v[142:145], v[98:113]
	s_setprio 0
	v_cmp_le_i32_e32 vcc, s38, v162
	v_cmp_lt_i32_e64 s[6:7], s55, v242
	v_cmp_gt_i32_e64 s[4:5], s67, v242
	s_and_b64 s[6:7], vcc, s[6:7]
	v_add_f32_e32 v2, 0x41000000, v249
	s_and_saveexec_b64 s[18:19], s[6:7]
	s_xor_b64 s[6:7], exec, s[18:19]
	s_cbranch_execz .LBB0_2273
	s_cmp_eq_u64 s[6:7], 0
	s_cbranch_scc1 .Lfast_cmp1
	s_nop 2
	v_max_f32_e32 v4, v98, v98
	v_max_f32_e32 v5, v82, v82
	v_max_f32_e32 v4, v5, v4
	v_max3_f32 v4, v4, v83, v99
	s_nop 0
	v_max3_f32 v4, v4, v84, v100
	s_nop 0
	v_max3_f32 v4, v4, v85, v101
	s_nop 0
	v_max3_f32 v4, v4, v86, v102
	s_nop 0
	v_max3_f32 v4, v4, v87, v103
	s_nop 0
	v_max3_f32 v4, v4, v88, v104
	s_nop 0
	v_max3_f32 v4, v4, v89, v105
	s_nop 0
	v_max3_f32 v4, v4, v90, v106
	s_nop 0
	v_max3_f32 v4, v4, v91, v107
	s_nop 0
	v_max3_f32 v4, v4, v92, v108
	s_nop 0
	v_max3_f32 v4, v4, v93, v109
	s_nop 0
	v_max3_f32 v4, v4, v94, v110
	s_nop 0
	v_max3_f32 v4, v4, v95, v111
	s_nop 0
	v_max3_f32 v4, v4, v96, v112
	s_nop 0
	v_max3_f32 v4, v4, v97, v113
	s_nop 0
	v_mov_b32_e32 v5, v4
	s_nop 1
	v_permlane32_swap_b32_e32 v4, v5
	v_max_f32_e32 v5, v5, v5
	v_max_f32_e32 v4, v4, v4
	v_max_f32_e32 v4, v4, v5
	v_mul_f32_e32 v4, 0x3e0293ee, v4
	v_cmp_gt_f32_e32 vcc, v4, v2
	s_nop 1
	v_cndmask_b32_e32 v250, v249, v4, vcc
	v_sub_f32_e32 v2, v249, v250
	v_exp_f32_e32 v2, v2
	s_nop 0
	v_cmp_neq_f32_e32 vcc, 1.0, v2
	s_cbranch_vccz .LBB0_2272
	v_pk_mul_f32 v[80:81], v[80:81], v[2:3] op_sel_hi:[1,0]
	v_pk_mul_f32 v[78:79], v[78:79], v[2:3] op_sel_hi:[1,0]
	v_pk_mul_f32 v[76:77], v[76:77], v[2:3] op_sel_hi:[1,0]
	v_pk_mul_f32 v[74:75], v[74:75], v[2:3] op_sel_hi:[1,0]
	v_pk_mul_f32 v[72:73], v[72:73], v[2:3] op_sel_hi:[1,0]
	v_pk_mul_f32 v[70:71], v[70:71], v[2:3] op_sel_hi:[1,0]
	v_pk_mul_f32 v[68:69], v[68:69], v[2:3] op_sel_hi:[1,0]
	v_pk_mul_f32 v[66:67], v[66:67], v[2:3] op_sel_hi:[1,0]
	v_pk_mul_f32 v[64:65], v[64:65], v[2:3] op_sel_hi:[1,0]
	v_pk_mul_f32 v[62:63], v[62:63], v[2:3] op_sel_hi:[1,0]
	v_pk_mul_f32 v[60:61], v[60:61], v[2:3] op_sel_hi:[1,0]
	v_pk_mul_f32 v[58:59], v[58:59], v[2:3] op_sel_hi:[1,0]
	v_pk_mul_f32 v[56:57], v[56:57], v[2:3] op_sel_hi:[1,0]
	v_pk_mul_f32 v[54:55], v[54:55], v[2:3] op_sel_hi:[1,0]
	v_pk_mul_f32 v[52:53], v[52:53], v[2:3] op_sel_hi:[1,0]
	v_pk_mul_f32 v[50:51], v[50:51], v[2:3] op_sel_hi:[1,0]
	v_pk_mul_f32 v[48:49], v[48:49], v[2:3] op_sel_hi:[1,0]
	v_pk_mul_f32 v[46:47], v[46:47], v[2:3] op_sel_hi:[1,0]
	v_pk_mul_f32 v[44:45], v[44:45], v[2:3] op_sel_hi:[1,0]
	v_pk_mul_f32 v[42:43], v[42:43], v[2:3] op_sel_hi:[1,0]
	v_pk_mul_f32 v[40:41], v[40:41], v[2:3] op_sel_hi:[1,0]
	v_pk_mul_f32 v[38:39], v[38:39], v[2:3] op_sel_hi:[1,0]
	v_pk_mul_f32 v[36:37], v[36:37], v[2:3] op_sel_hi:[1,0]
	v_pk_mul_f32 v[34:35], v[34:35], v[2:3] op_sel_hi:[1,0]
	v_pk_mul_f32 v[32:33], v[32:33], v[2:3] op_sel_hi:[1,0]
	v_pk_mul_f32 v[30:31], v[30:31], v[2:3] op_sel_hi:[1,0]
	v_pk_mul_f32 v[28:29], v[28:29], v[2:3] op_sel_hi:[1,0]
	v_pk_mul_f32 v[26:27], v[26:27], v[2:3] op_sel_hi:[1,0]
	v_pk_mul_f32 v[24:25], v[24:25], v[2:3] op_sel_hi:[1,0]
	v_pk_mul_f32 v[22:23], v[22:23], v[2:3] op_sel_hi:[1,0]
	v_pk_mul_f32 v[20:21], v[20:21], v[2:3] op_sel_hi:[1,0]
	v_pk_mul_f32 v[18:19], v[18:19], v[2:3] op_sel_hi:[1,0]

; template <int MODE, int DK, bool PASS2> ...
;     ...
;         if (has) write_tile(buf ^ 1);
;         if (MODE == M_FOX) { if (__syncthreads_and(dead ? 1 : 0)) break; }
;         else __syncthreads();
;         if (!has) break;
;         j = jn; buf ^= 1;
;     }
.Lpostpv_cmp1:
	v_mov_b32_e32 v249, v250
	v_mov_b32_e32 v248, v251
	s_or_b64 exec, exec, s[16:17]
	s_andn2_b64 vcc, exec, s[14:15]
	s_xor_b32 s39, s39, 1
	s_cbranch_vccnz .LBB0_2264

; #define LAS __attribute__((address_space(3)))
; __device__ __forceinline__ float fexp2(float x) { return __builtin_amdgcn_exp2f(x); }
; __device__ __forceinline__ float fmax3(float a, float b, float c) { float d; asm("v_max3_f32 %0, %1, %2, %3" : "=v"(d) : "v"(a), "v"(b), "v"(c)); return d; }
; template <int MODE, int DK, bool PASS2> ...
;     ...
;                     float mx = fmaxf(s0[0], s1[0]);
; #pragma unroll
;                     for (int r = 1; r < 16; ++r) mx = fmax3(mx, s0[r], s1[r]);
;                     if (MODE == M_SLC) mx = selbit ? mx : NEG;
;                     mx = xhalf_max(mx);
;                     const float mxs = mx * sl2;
;                     const float mn = (mxs > m_run + 8.0f) ? mxs : m_run;
;                     const float alpha = fexp2(m_run - mn);
;                     m_run = mn;
;                     float nm = -mn;
;                     if (MODE == M_SLC) nm = selbit ? nm : -__builtin_inff();
;                     float ps0 = 0.f, ps1 = 0.f;
; #pragma unroll
;                     for (int r = 0; r < 16; ++r) {
;                         s0[r] = fexp2(__builtin_fmaf(s0[r], sl2, nm)); s1[r] = fexp2(__builtin_fmaf(s1[r], sl2, nm));
;                         ps0 += s0[r]; ps1 += s1[r];
;                     }
;                     l_run = l_run * alpha + (ps0 + ps1);
;                     if (__builtin_amdgcn_ballot_w64(alpha != 1.0f) != 0ull) {
; #pragma unroll
;                         for (int db = 0; db < 4; ++db)
; #pragma unroll
;                             for (int r = 0; r < 16; ++r) O[db][r] *= alpha;
;                     }
;     ...
;                     const LAS unsigned char* vb = lds + F_VB0 + buf * F_VBS + ql * 144 + g * 16;
;                     __builtin_amdgcn_s_setprio(1);
; #pragma unroll
;                     for (int db = 0; db < 4; ++db)
; #pragma unroll
;                         for (int k2 = 0; k2 < 4; ++k2) {
;                             const bf16x8 vf = *(const LAS bf16x8*)(vb + db * 32 * 144 + k2 * 32);
.Lfast_cmp1:
	s_mul_i32 s98, s39, 0x4800
	v_add_u32_e32 v216, s98, v240
	ds_read_b128 v[204:207], v216 offset:34816
	ds_read_b128 v[208:211], v216 offset:39424
	ds_read_b128 v[212:215], v216 offset:44032
	v_max_f32_e32 v200, v82, v83
	v_max_f32_e32 v201, v98, v99
	v_max3_f32 v200, v200, v84, v85
	v_max3_f32 v201, v201, v100, v101
	v_max3_f32 v200, v200, v86, v87
	v_max3_f32 v201, v201, v102, v103
	v_max3_f32 v200, v200, v88, v89
	v_max3_f32 v201, v201, v104, v105
	v_max3_f32 v200, v200, v90, v91
	v_max3_f32 v201, v201, v106, v107
	v_max3_f32 v200, v200, v92, v93
	v_max3_f32 v201, v201, v108, v109
	v_max3_f32 v200, v200, v94, v95
	v_max3_f32 v201, v201, v110, v111
	v_max3_f32 v200, v200, v96, v97
	v_max3_f32 v201, v201, v112, v113
	v_max_f32_e32 v200, v200, v201
	v_mov_b32_e32 v201, v200
	s_nop 1
	v_permlane32_swap_b32_e32 v200, v201
	v_max_f32_e32 v200, v200, v201
	v_mul_f32_e32 v200, 0x3e0293ee, v200
	v_cmp_gt_f32_e32 vcc, v200, v2
	s_nop 1
	v_cndmask_b32_e32 v250, v249, v200, vcc
	v_sub_f32_e32 v201, v249, v250
	v_exp_f32_e32 v2, v201
	s_nop 0
	v_cmp_neq_f32_e32 vcc, 1.0, v2
	s_cbranch_vccz .Lfast_cmp1_norescale
	v_pk_mul_f32 v[80:81], v[80:81], v[2:3] op_sel_hi:[1,0]
	v_pk_mul_f32 v[78:79], v[78:79], v[2:3] op_sel_hi:[1,0]
	v_pk_mul_f32 v[76:77], v[76:77], v[2:3] op_sel_hi:[1,0]
	v_pk_mul_f32 v[74:75], v[74:75], v[2:3] op_sel_hi:[1,0]
	v_pk_mul_f32 v[72:73], v[72:73], v[2:3] op_sel_hi:[1,0]
	v_pk_mul_f32 v[70:71], v[70:71], v[2:3] op_sel_hi:[1,0]
	v_pk_mul_f32 v[68:69], v[68:69], v[2:3] op_sel_hi:[1,0]
	v_pk_mul_f32 v[66:67], v[66:67], v[2:3] op_sel_hi:[1,0]
	v_pk_mul_f32 v[64:65], v[64:65], v[2:3] op_sel_hi:[1,0]
	v_pk_mul_f32 v[62:63], v[62:63], v[2:3] op_sel_hi:[1,0]
	v_pk_mul_f32 v[60:61], v[60:61], v[2:3] op_sel_hi:[1,0]
	v_pk_mul_f32 v[58:59], v[58:59], v[2:3] op_sel_hi:[1,0]
	v_pk_mul_f32 v[56:57], v[56:57], v[2:3] op_sel_hi:[1,0]
	v_pk_mul_f32 v[54:55], v[54:55], v[2:3] op_sel_hi:[1,0]
	v_pk_mul_f32 v[52:53], v[52:53], v[2:3] op_sel_hi:[1,0]
	v_pk_mul_f32 v[50:51], v[50:51], v[2:3] op_sel_hi:[1,0]
	v_pk_mul_f32 v[48:49], v[48:49], v[2:3] op_sel_hi:[1,0]
	v_pk_mul_f32 v[46:47], v[46:47], v[2:3] op_sel_hi:[1,0]
	v_pk_mul_f32 v[44:45], v[44:45], v[2:3] op_sel_hi:[1,0]
	v_pk_mul_f32 v[42:43], v[42:43], v[2:3] op_sel_hi:[1,0]
	v_pk_mul_f32 v[40:41], v[40:41], v[2:3] op_sel_hi:[1,0]
	v_pk_mul_f32 v[38:39], v[38:39], v[2:3] op_sel_hi:[1,0]
	v_pk_mul_f32 v[36:37], v[36:37], v[2:3] op_sel_hi:[1,0]
	v_pk_mul_f32 v[34:35], v[34:35], v[2:3] op_sel_hi:[1,0]
	v_pk_mul_f32 v[32:33], v[32:33], v[2:3] op_sel_hi:[1,0]
	v_pk_mul_f32 v[30:31], v[30:31], v[2:3] op_sel_hi:[1,0]
	v_pk_mul_f32 v[28:29], v[28:29], v[2:3] op_sel_hi:[1,0]
	v_pk_mul_f32 v[26:27], v[26:27], v[2:3] op_sel_hi:[1,0]
	v_pk_mul_f32 v[24:25], v[24:25], v[2:3] op_sel_hi:[1,0]
	v_pk_mul_f32 v[22:23], v[22:23], v[2:3] op_sel_hi:[1,0]
	v_pk_mul_f32 v[20:21], v[20:21], v[2:3] op_sel_hi:[1,0]
	v_pk_mul_f32 v[18:19], v[18:19], v[2:3] op_sel_hi:[1,0]
; #define LAS __attribute__((address_space(3)))
; __device__ __forceinline__ unsigned pack2(float lo, float hi) { unsigned r; asm volatile("v_cvt_pk_bf16_f32 %0, %1, %2" : "=v"(r) : "v"(lo), "v"(hi)); return r; }
; __device__ __forceinline__ float fexp2(float x) { return __builtin_amdgcn_exp2f(x); }
; __device__ __forceinline__ f32x16 mfma32(bf16x8 a, bf16x8 b, f32x16 c) { return __builtin_amdgcn_mfma_f32_32x32x16_bf16(a, b, c, 0, 0, 0); }
; template <int MODE, int DK, bool PASS2> ...
;     ...
;                     float ps0 = 0.f, ps1 = 0.f;
; #pragma unroll
;                     for (int r = 0; r < 16; ++r) {
;                         s0[r] = fexp2(__builtin_fmaf(s0[r], sl2, nm)); s1[r] = fexp2(__builtin_fmaf(s1[r], sl2, nm));
;                         ps0 += s0[r]; ps1 += s1[r];
;                     }
;                     l_run = l_run * alpha + (ps0 + ps1);
;     ...
;                 if (!PASS2) {
;                     bf16x8 pf[4];
; #pragma unroll
;                     for (int k2 = 0; k2 < 4; ++k2) {
;                         u32x4 pk;
; #pragma unroll
;                         for (int e = 0; e < 4; ++e) pk[e] = (k2 < 2) ? pack2(s0[(k2 & 1) * 8 + 2 * e], s0[(k2 & 1) * 8 + 2 * e + 1]) : pack2(s1[(k2 & 1) * 8 + 2 * e], s1[(k2 & 1) * 8 + 2 * e + 1]);
;                         pf[k2] = __builtin_bit_cast(bf16x8, pk);
;                     }
;                     const LAS unsigned char* vb = lds + F_VB0 + buf * F_VBS + ql * 144 + g * 16;
;                     __builtin_amdgcn_s_setprio(1);
; #pragma unroll
;                     for (int db = 0; db < 4; ++db)
; #pragma unroll
;                         for (int k2 = 0; k2 < 4; ++k2) {
;                             const bf16x8 vf = *(const LAS bf16x8*)(vb + db * 32 * 144 + k2 * 32);
;                             O[db] = mfma32(vf, pf[k2], O[db]);
;                             if (k2 == 3 && (db & 1)) __builtin_amdgcn_sched_barrier(0);
;                         }
;                     __builtin_amdgcn_s_setprio(0);
.Lfast_cmp1_norescale:
	v_fma_f32 v12, v82, s34, -v250
	v_fma_f32 v13, v83, s34, -v250
	v_exp_f32_e32 v4, v12
	v_exp_f32_e32 v5, v13
	v_fma_f32 v14, v84, s34, -v250
	v_fma_f32 v15, v85, s34, -v250
	v_exp_f32_e32 v6, v14
	v_exp_f32_e32 v7, v15
	v_add_f32_e32 v16, v4, v5
	v_fma_f32 v12, v86, s34, -v250
	v_fma_f32 v13, v87, s34, -v250
	v_exp_f32_e32 v8, v12
	v_exp_f32_e32 v9, v13
	v_cvt_pk_bf16_f32 v82, v4, v5
	v_add_f32_e32 v16, v16, v6
	v_fma_f32 v14, v88, s34, -v250
	v_add_f32_e32 v16, v16, v7
	v_fma_f32 v15, v89, s34, -v250
	v_exp_f32_e32 v10, v14
	v_exp_f32_e32 v11, v15
	v_cvt_pk_bf16_f32 v83, v6, v7
	v_add_f32_e32 v16, v16, v8
	v_add_f32_e32 v16, v16, v9
	v_cvt_pk_bf16_f32 v84, v8, v9
	v_add_f32_e32 v16, v16, v10
	v_add_f32_e32 v16, v16, v11
	v_cvt_pk_bf16_f32 v85, v10, v11
	s_setprio 1
	v_fma_f32 v12, v90, s34, -v250
	v_fma_f32 v13, v91, s34, -v250
	s_waitcnt lgkmcnt(2)
	v_mfma_f32_32x32x16_bf16 v[66:81], v[204:207], v[82:85], v[66:81]
	v_exp_f32_e32 v4, v12
	v_exp_f32_e32 v5, v13
	v_fma_f32 v14, v92, s34, -v250
	v_fma_f32 v15, v93, s34, -v250
	v_exp_f32_e32 v6, v14
	v_exp_f32_e32 v7, v15
	v_add_f32_e32 v16, v16, v4
	s_waitcnt lgkmcnt(1)
	v_mfma_f32_32x32x16_bf16 v[50:65], v[208:211], v[82:85], v[50:65]
	ds_read_b128 v[204:207], v216 offset:48640
	v_fma_f32 v12, v94, s34, -v250
	v_add_f32_e32 v16, v16, v5
	v_fma_f32 v13, v95, s34, -v250
	v_exp_f32_e32 v8, v12
	v_exp_f32_e32 v9, v13
	v_cvt_pk_bf16_f32 v90, v4, v5
	v_add_f32_e32 v16, v16, v6
	s_waitcnt lgkmcnt(1)
	v_mfma_f32_32x32x16_bf16 v[34:49], v[212:215], v[82:85], v[34:49]
	ds_read_b128 v[208:211], v216 offset:34848
	v_fma_f32 v14, v96, s34, -v250
	v_add_f32_e32 v16, v16, v7
	v_fma_f32 v15, v97, s34, -v250
	v_exp_f32_e32 v10, v14
	v_exp_f32_e32 v11, v15
	v_cvt_pk_bf16_f32 v91, v6, v7
	v_add_f32_e32 v16, v16, v8
	s_waitcnt lgkmcnt(1)
	v_mfma_f32_32x32x16_bf16 v[18:33], v[204:207], v[82:85], v[18:33]
	ds_read_b128 v[212:215], v216 offset:39456
	v_add_f32_e32 v16, v16, v9
	v_cvt_pk_bf16_f32 v92, v8, v9
	v_add_f32_e32 v16, v16, v10
	v_add_f32_e32 v16, v16, v11
	v_cvt_pk_bf16_f32 v93, v10, v11
	v_fma_f32 v12, v98, s34, -v250
	v_fma_f32 v13, v99, s34, -v250
	s_waitcnt lgkmcnt(1)
	v_mfma_f32_32x32x16_bf16 v[66:81], v[208:211], v[90:93], v[66:81]
	ds_read_b128 v[204:207], v216 offset:44064
	v_exp_f32_e32 v4, v12
	v_exp_f32_e32 v5, v13
	v_fma_f32 v14, v100, s34, -v250
	v_fma_f32 v15, v101, s34, -v250
	v_exp_f32_e32 v6, v14
	v_exp_f32_e32 v7, v15
	v_add_f32_e32 v17, v4, v5
	s_waitcnt lgkmcnt(1)
	v_mfma_f32_32x32x16_bf16 v[50:65], v[212:215], v[90:93], v[50:65]
	ds_read_b128 v[208:211], v216 offset:48672
	v_fma_f32 v12, v102, s34, -v250
	v_fma_f32 v13, v103, s34, -v250
	v_exp_f32_e32 v8, v12
	v_exp_f32_e32 v9, v13
	v_cvt_pk_bf16_f32 v98, v4, v5
	v_add_f32_e32 v17, v17, v6
	v_fma_f32 v14, v104, s34, -v250
	s_waitcnt lgkmcnt(1)
	v_mfma_f32_32x32x16_bf16 v[34:49], v[204:207], v[90:93], v[34:49]
	ds_read_b128 v[212:215], v216 offset:34880
	v_add_f32_e32 v17, v17, v7
	v_fma_f32 v15, v105, s34, -v250
	v_exp_f32_e32 v10, v14
	v_exp_f32_e32 v11, v15
	v_cvt_pk_bf16_f32 v99, v6, v7
	v_add_f32_e32 v17, v17, v8
	v_add_f32_e32 v17, v17, v9
	s_waitcnt lgkmcnt(1)
	v_mfma_f32_32x32x16_bf16 v[18:33], v[208:211], v[90:93], v[18:33]
	ds_read_b128 v[204:207], v216 offset:39488
	v_cvt_pk_bf16_f32 v100, v8, v9
	v_add_f32_e32 v17, v17, v10
	v_add_f32_e32 v17, v17, v11
	v_cvt_pk_bf16_f32 v101, v10, v11
	v_fma_f32 v12, v106, s34, -v250
	v_fma_f32 v13, v107, s34, -v250
	s_waitcnt lgkmcnt(1)
	v_mfma_f32_32x32x16_bf16 v[66:81], v[212:215], v[98:101], v[66:81]
	ds_read_b128 v[208:211], v216 offset:44096
	v_exp_f32_e32 v4, v12
	v_exp_f32_e32 v5, v13
	v_fma_f32 v14, v108, s34, -v250
	v_fma_f32 v15, v109, s34, -v250
	v_exp_f32_e32 v6, v14
	v_exp_f32_e32 v7, v15
	v_add_f32_e32 v17, v17, v4
	s_waitcnt lgkmcnt(1)
	v_mfma_f32_32x32x16_bf16 v[50:65], v[204:207], v[98:101], v[50:65]
	ds_read_b128 v[212:215], v216 offset:48704
	v_fma_f32 v12, v110, s34, -v250
	v_add_f32_e32 v17, v17, v5
	v_fma_f32 v13, v111, s34, -v250
	v_exp_f32_e32 v8, v12
	v_exp_f32_e32 v9, v13
	v_cvt_pk_bf16_f32 v106, v4, v5
	v_add_f32_e32 v17, v17, v6
	s_waitcnt lgkmcnt(1)
	v_mfma_f32_32x32x16_bf16 v[34:49], v[208:211], v[98:101], v[34:49]
	ds_read_b128 v[204:207], v216 offset:34912
	v_fma_f32 v14, v112, s34, -v250
	v_add_f32_e32 v17, v17, v7
	v_fma_f32 v15, v113, s34, -v250
	v_exp_f32_e32 v10, v14
	v_exp_f32_e32 v11, v15
	v_cvt_pk_bf16_f32 v107, v6, v7
	v_add_f32_e32 v17, v17, v8
	s_waitcnt lgkmcnt(1)
	v_mfma_f32_32x32x16_bf16 v[18:33], v[212:215], v[98:101], v[18:33]
	ds_read_b128 v[208:211], v216 offset:39520
	v_add_f32_e32 v17, v17, v9
	v_cvt_pk_bf16_f32 v108, v8, v9
	v_add_f32_e32 v17, v17, v10
	v_add_f32_e32 v17, v17, v11
	v_cvt_pk_bf16_f32 v109, v10, v11
	v_add_f32_e32 v251, v16, v17
	s_waitcnt lgkmcnt(1)
	v_mfma_f32_32x32x16_bf16 v[66:81], v[204:207], v[106:109], v[66:81]
	ds_read_b128 v[212:215], v216 offset:44128
	v_fmac_f32_e32 v251, v248, v2
	s_waitcnt lgkmcnt(1)
	v_mfma_f32_32x32x16_bf16 v[50:65], v[208:211], v[106:109], v[50:65]
	ds_read_b128 v[204:207], v216 offset:48736
	s_waitcnt lgkmcnt(1)
	v_mfma_f32_32x32x16_bf16 v[34:49], v[212:215], v[106:109], v[34:49]
	s_waitcnt lgkmcnt(0)
	v_mfma_f32_32x32x16_bf16 v[18:33], v[204:207], v[106:109], v[18:33]
	s_setprio 0
	s_branch .Lpostpv_cmp1
